# hand-written LDS-DMA attention items + V^T stored in 4KiB key-block tiles by the projection epilogue
# speedup vs baseline: 1.0463x; 1.0025x over previous
; DI u32x4 pack8(f32x4 a, f32x4 b) { u32x4 w; w.x = pk2(a[0], a[1]); w.y = pk2(a[2], a[3]); w.z = pk2(b[0], b[1]); w.w = pk2(b[2], b[3]); return w; }
; template <int PH>
; DI void epilogue(const Params& p, const f32x4 (&acc)[2][2][4][2], const Unit& u, int wr, int wc, int fr, int fq) {
;     ...
;                         const int tc = 128 * bj + 32 * wc + 8 * fq;
;                         const f32x4 v0 = acc[ai][bj][m][0], v1 = acc[ai][bj][m][1];
;                         const u32x4 w = pack8(v0, v1);
;                         if (kind == K_MEMV) {
;                             const int b = u.pm;
;                             *(u32x4*)((bf16_t*)(ws + OFF_MVT) + (size_t)(b * 256 + f) * 256 + tc) = w;
;                             float* o = p.out + O_MVP + (size_t)(b * 256 + tc) * 256 + f;
; #pragma unroll
;                             for (int j = 0; j < 4; ++j) { o[(size_t)j * 256] = v0[j]; o[(size_t)(4 + j) * 256] = v1[j]; }
;                         } else if (u.pm < 64) {
;                             const int b = u.pm >> 5, t = (u.pm & 31) * 256 + tc;
;                             if (kind == K_VA) *(u32x4*)((bf16_t*)(ws + OFF_VAT) + (size_t)(b * 512 + f) * VLD + t) = w;
.LBB0_523:
	s_andn2_b64 vcc, exec, s[4:5]
	s_cbranch_vccnz .LBB0_525
	v_add_u32_e32 v135, s17, v132
	v_lshlrev_b32_e32 v152, 1, v134
	v_lshrrev_b32_e32 v136, 6, v135
	v_lshlrev_b32_e32 v136, 20, v136
	v_and_b32_e32 v137, 63, v135
	v_lshl_add_u32 v136, v137, 6, v136
	v_lshrrev_b32_e32 v137, 6, v152
	v_lshl_add_u32 v136, v137, 12, v136
	v_and_b32_e32 v137, 62, v152
	v_add_u32_e32 v136, v136, v137
	global_store_dwordx4 v136, v[128:131], s[28:29]

; DI u32x4 pack8(f32x4 a, f32x4 b) { u32x4 w; w.x = pk2(a[0], a[1]); w.y = pk2(a[2], a[3]); w.z = pk2(b[0], b[1]); w.w = pk2(b[2], b[3]); return w; }
; template <int PH>
; DI void epilogue(const Params& p, const f32x4 (&acc)[2][2][4][2], const Unit& u, int wr, int wc, int fr, int fq) {
;     ...
;                         const int tc = 128 * bj + 32 * wc + 8 * fq;
;                         const f32x4 v0 = acc[ai][bj][m][0], v1 = acc[ai][bj][m][1];
;                         const u32x4 w = pack8(v0, v1);
;                         if (kind == K_MEMV) {
;                             const int b = u.pm;
;                             *(u32x4*)((bf16_t*)(ws + OFF_MVT) + (size_t)(b * 256 + f) * 256 + tc) = w;
;                             float* o = p.out + O_MVP + (size_t)(b * 256 + tc) * 256 + f;
; #pragma unroll
;                             for (int j = 0; j < 4; ++j) { o[(size_t)j * 256] = v0[j]; o[(size_t)(4 + j) * 256] = v1[j]; }
;                         } else if (u.pm < 64) {
;                             const int b = u.pm >> 5, t = (u.pm & 31) * 256 + tc;
;                             if (kind == K_VA) *(u32x4*)((bf16_t*)(ws + OFF_VAT) + (size_t)(b * 512 + f) * VLD + t) = w;
.LBB0_540:
	s_andn2_b64 vcc, exec, s[68:69]
	s_cbranch_vccnz .LBB0_542
	v_add_u32_e32 v135, s17, v132
	v_add_lshl_u32 v152, s38, v199, 1
	v_lshrrev_b32_e32 v136, 6, v135
	v_lshlrev_b32_e32 v136, 20, v136
	v_and_b32_e32 v137, 63, v135
	v_lshl_add_u32 v136, v137, 6, v136
	v_lshrrev_b32_e32 v137, 6, v152
	v_lshl_add_u32 v136, v137, 12, v136
	v_and_b32_e32 v137, 62, v152
	v_add_u32_e32 v136, v136, v137
	v_add_u32_e32 v136, 0x4000, v136
	global_store_dwordx4 v136, v[128:131], s[28:29]

; DI u32x4 pack8(f32x4 a, f32x4 b) { u32x4 w; w.x = pk2(a[0], a[1]); w.y = pk2(a[2], a[3]); w.z = pk2(b[0], b[1]); w.w = pk2(b[2], b[3]); return w; }
; template <int PH>
; DI void epilogue(const Params& p, const f32x4 (&acc)[2][2][4][2], const Unit& u, int wr, int wc, int fr, int fq) {
;     ...
;                         const int tc = 128 * bj + 32 * wc + 8 * fq;
;                         const f32x4 v0 = acc[ai][bj][m][0], v1 = acc[ai][bj][m][1];
;                         const u32x4 w = pack8(v0, v1);
;                         if (kind == K_MEMV) {
;                             const int b = u.pm;
;                             *(u32x4*)((bf16_t*)(ws + OFF_MVT) + (size_t)(b * 256 + f) * 256 + tc) = w;
;                             float* o = p.out + O_MVP + (size_t)(b * 256 + tc) * 256 + f;
; #pragma unroll
;                             for (int j = 0; j < 4; ++j) { o[(size_t)j * 256] = v0[j]; o[(size_t)(4 + j) * 256] = v1[j]; }
;                         } else if (u.pm < 64) {
;                             const int b = u.pm >> 5, t = (u.pm & 31) * 256 + tc;
;                             if (kind == K_VA) *(u32x4*)((bf16_t*)(ws + OFF_VAT) + (size_t)(b * 512 + f) * VLD + t) = w;
.LBB0_557:
	s_andn2_b64 vcc, exec, s[68:69]
	s_cbranch_vccnz .LBB0_559
	v_add_u32_e32 v135, s17, v132
	v_lshlrev_b32_e32 v152, 1, v134
	v_lshrrev_b32_e32 v136, 6, v135
	v_lshlrev_b32_e32 v136, 20, v136
	v_and_b32_e32 v137, 63, v135
	v_lshl_add_u32 v136, v137, 6, v136
	v_lshrrev_b32_e32 v137, 6, v152
	v_lshl_add_u32 v136, v137, 12, v136
	v_and_b32_e32 v137, 62, v152
	v_add_u32_e32 v136, v136, v137
	global_store_dwordx4 v136, v[128:131], s[28:29]

; DI u32x4 pack8(f32x4 a, f32x4 b) { u32x4 w; w.x = pk2(a[0], a[1]); w.y = pk2(a[2], a[3]); w.z = pk2(b[0], b[1]); w.w = pk2(b[2], b[3]); return w; }
; template <int PH>
; DI void epilogue(const Params& p, const f32x4 (&acc)[2][2][4][2], const Unit& u, int wr, int wc, int fr, int fq) {
;     ...
;                         const int tc = 128 * bj + 32 * wc + 8 * fq;
;                         const f32x4 v0 = acc[ai][bj][m][0], v1 = acc[ai][bj][m][1];
;                         const u32x4 w = pack8(v0, v1);
;                         if (kind == K_MEMV) {
;                             const int b = u.pm;
;                             *(u32x4*)((bf16_t*)(ws + OFF_MVT) + (size_t)(b * 256 + f) * 256 + tc) = w;
;                             float* o = p.out + O_MVP + (size_t)(b * 256 + tc) * 256 + f;
; #pragma unroll
;                             for (int j = 0; j < 4; ++j) { o[(size_t)j * 256] = v0[j]; o[(size_t)(4 + j) * 256] = v1[j]; }
;                         } else if (u.pm < 64) {
;                             const int b = u.pm >> 5, t = (u.pm & 31) * 256 + tc;
;                             if (kind == K_VA) *(u32x4*)((bf16_t*)(ws + OFF_VAT) + (size_t)(b * 512 + f) * VLD + t) = w;
.LBB0_778:
	s_andn2_b64 vcc, exec, s[4:5]
	s_cbranch_vccnz .LBB0_780
	v_add_u32_e32 v135, s8, v132
	v_add_lshl_u32 v152, s9, v199, 1
	v_lshrrev_b32_e32 v136, 6, v135
	v_lshlrev_b32_e32 v136, 20, v136
	v_and_b32_e32 v137, 63, v135
	v_lshl_add_u32 v136, v137, 6, v136
	v_lshrrev_b32_e32 v137, 6, v152
	v_lshl_add_u32 v136, v137, 12, v136
	v_and_b32_e32 v137, 62, v152
	v_add_u32_e32 v136, v136, v137
	v_add_u32_e32 v136, 0x4000, v136
	global_store_dwordx4 v136, v[128:131], s[28:29]

; DI void attn_item(const AttnItem& it, LAS unsigned char* wl, int lane) {
;     const int qi = lane & 31, hh = lane >> 5;
;     const int qr = qi < it.nq ? qi : it.nq - 1;
;     bf16x8 bq[4];
; #pragma unroll
;     for (int kk = 0; kk < 4; ++kk) bq[kk] = *(const bf16x8*)(it.q + (size_t)qr * it.qld + 16 * kk + 8 * hh);
;     float mrun = -1e30f, lsum = 0.f;
;     f32x16 o0, o1;
; #pragma unroll
;     for (int r = 0; r < 16; ++r) { o0[r] = 0.f; o1[r] = 0.f; }
;     const int krow = lane >> 3, kch = lane & 7, vrow = lane >> 2, vch = lane & 3;
;     const bf16_t* kg = it.k + (size_t)krow * it.kld + 8 * kch;
;     const bf16_t* vg = it.vt + (size_t)vrow * it.vtld + 8 * vch;
;     LAS unsigned char* Kl = wl; LAS unsigned char* Vl = wl + 4608;
;     const unsigned kw = krow * 144 + kch * 16, vw = vrow * 80 + vch * 16;
;     const unsigned kr = qi * 144 + hh * 16, vr = qi * 80 + hh * 8;
;     u32x4 kA[4], vA[4], kB[4], vB[4];
; DI void p2_mixers(const Params& p, LAS unsigned char* lds) {
;     ...
;         AttnItem a;
;         a.qld = 512; a.kld = 512; a.zold = 512;
;         if (it < 4096) {
;             const int head = it & 7, half = (it >> 3) & 1, c = (it >> 4) & 127, b = it >> 11;
;             const int cs = c > 8 ? c - 8 : 0, kstart = 64 * cs, tq = b * 8192 + 64 * c + 32 * half;
;             a.q = (const bf16_t*)(ws + OFF_QA) + (size_t)tq * 512 + head * 64; a.nq = 32;
;             a.k = (const bf16_t*)(ws + OFF_KA) + (size_t)(b * 8192 + kstart) * 512 + head * 64;
;             a.vt = (const bf16_t*)(ws + OFF_VAT) + (size_t)(b * 512 + head * 64) * VLD + kstart; a.vtld = VLD;
;             a.nkeys = 64 * (c - cs + 1); a.nkb = a.nkeys >> 5;
;             a.bias = tab + head * 257; a.qpos0 = 64 * c + 32 * half - kstart;
;             a.zo = (bf16_t*)(ws + OFF_ZA) + (size_t)tq * 512 + head * 64;
;         } else {
;             const int j = it - 4096, head = j & 7, sb = j >> 3, tq = T_P + 16 * sb;
;             a.q = (const bf16_t*)(ws + OFF_QA) + (size_t)tq * 512 + head * 64; a.nq = 16;
;             a.k = (const bf16_t*)(ws + OFF_KS) + (size_t)sb * 528 * 512 + head * 64;
;             a.vt = (const bf16_t*)(ws + OFF_VST) + (size_t)(sb * 512 + head * 64) * 528; a.vtld = 528;
;             a.nkeys = 528; a.nkb = 17;
;             a.bias = tab + head * 257; a.qpos0 = 512;
;             a.zo = (bf16_t*)(ws + OFF_ZA) + (size_t)tq * 512 + head * 64;
;         }
.LBB0_937:
	s_cmpk_gt_i32 s61, 0xfff
	s_cbranch_scc1 .Lat_band_s2_1
	s_and_b32 s12, s61, 7
	s_bfe_u32 s13, s61, 0x10003
	s_bfe_u32 s14, s61, 0x70004
	s_lshr_b32 s15, s61, 11
	s_sub_u32 s16, s14, 8
	s_max_i32 s16, s16, 0
	s_lshl_b32 s17, s16, 6
	s_lshl_b32 s18, s15, 13
	s_lshl_b32 s19, s14, 6
	s_add_i32 s19, s19, s18
	s_lshl_b32 s20, s13, 5
	s_add_i32 s19, s19, s20
	s_lshl_b32 s21, s12, 7
	s_lshl_b32 s32, s19, 10
	s_add_i32 s32, s32, s21
	s_add_u32 s50, s44, 0x3600000
	s_addc_u32 s51, s45, 0
	s_add_u32 s50, s50, s32
	s_addc_u32 s51, s51, 0
	s_add_u32 s56, s44, 0x87d0000
	s_addc_u32 s57, s45, 0
	s_add_u32 s56, s56, s32
	s_addc_u32 s57, s57, 0
	s_add_i32 s32, s18, s17
	s_lshl_b32 s32, s32, 10
	s_add_i32 s32, s32, s21
	s_add_u32 s52, s44, 0x4680000
	s_addc_u32 s53, s45, 0
	s_add_u32 s52, s52, s32
	s_addc_u32 s53, s53, 0
	s_lshl_b32 s32, s15, 3
	s_add_i32 s32, s32, s12
	s_lshl_b32 s32, s32, 8
	s_lshr_b32 s39, s17, 5
	s_add_i32 s32, s32, s39
	s_lshl_b32 s32, s32, 12
	s_add_u32 s54, s44, 0x5680000
	s_addc_u32 s55, s45, 0
	s_add_u32 s54, s54, s32
	s_addc_u32 s55, s55, 0
	s_sub_i32 s32, s14, s16
	s_add_i32 s32, s32, 1
	s_lshl_b32 s64, s32, 6
	s_lshr_b32 s65, s64, 5
	s_sub_i32 s32, s19, s18
	s_sub_i32 s66, s32, s17
	s_mov_b32 s63, 32
	s_movk_i32 s59, 0x40
	s_movk_i32 s84, 0x1000
	s_branch .Lat_band_done_2
.Lat_band_s2_1:
	s_add_i32 s13, s61, 0xfffff000
	s_and_b32 s12, s13, 7
	s_lshr_b32 s14, s13, 3
	s_lshl_b32 s19, s14, 4
	s_add_i32 s19, s19, 0x4000
	s_lshl_b32 s21, s12, 7
	s_lshl_b32 s32, s19, 10
	s_add_i32 s32, s32, s21
	s_add_u32 s50, s44, 0x3600000
	s_addc_u32 s51, s45, 0
	s_add_u32 s50, s50, s32
	s_addc_u32 s51, s51, 0
	s_add_u32 s56, s44, 0x87d0000
	s_addc_u32 s57, s45, 0
	s_add_u32 s56, s56, s32
	s_addc_u32 s57, s57, 0
	s_mul_i32 s32, s14, 0x84000
	s_add_i32 s32, s32, s21
	s_add_u32 s52, s44, 0x66c0000
	s_addc_u32 s53, s45, 0
	s_add_u32 s52, s52, s32
	s_addc_u32 s53, s53, 0
	s_lshl_b32 s32, s14, 9
	s_lshl_b32 s39, s12, 6
	s_add_i32 s32, s32, s39
	s_mul_i32 s32, s32, 0x420
	s_add_u32 s54, s44, 0x7748000
	s_addc_u32 s55, s45, 0
	s_add_u32 s54, s54, s32
	s_addc_u32 s55, s55, 0
	s_movk_i32 s64, 0x210
	s_mov_b32 s65, 17
	s_movk_i32 s66, 0x200
	s_mov_b32 s63, 16
	s_movk_i32 s59, 0x420
	s_movk_i32 s84, 0x40
.Lat_band_done_2:
	s_movk_i32 s58, 0x400
	s_mul_i32 s67, s12, 0x404
	s_mov_b32 s68, 1
	s_mov_b32 s69, 0
	s_branch .Lat_entry
.Lat_entry:
	v_and_b32_e32 v108, 31, v203
	v_bfe_u32 v109, v203, 5, 1
	v_and_b32_e32 v110, 63, v203
	s_add_i32 s70, s49, 0x2100
	s_add_i32 s77, s63, -1
	v_min_u32_e32 v97, s77, v108
	v_mul_lo_u32 v97, v97, s58
	v_lshl_add_u32 v97, v109, 4, v97
	global_load_dwordx4 v[0:3], v97, s[50:51]
	global_load_dwordx4 v[4:7], v97, s[50:51] offset:32
	global_load_dwordx4 v[8:11], v97, s[50:51] offset:64
	global_load_dwordx4 v[12:15], v97, s[50:51] offset:96
	v_lshrrev_b32_e32 v96, 4, v110
	v_and_b32_e32 v104, 7, v110
	v_lshrrev_b32_e32 v100, 3, v110
	v_xor_b32_e32 v101, v104, v96
	v_add_u32_e32 v102, 0, v100
	v_mul_lo_u32 v102, v102, s58
	v_lshl_add_u32 v228, v101, 4, v102
	v_xor_b32_e32 v101, v104, v96
	v_xor_b32_e32 v101, 4, v101
	v_add_u32_e32 v102, 8, v100
	v_mul_lo_u32 v102, v102, s58
	v_lshl_add_u32 v229, v101, 4, v102
	v_xor_b32_e32 v101, v104, v96
	v_add_u32_e32 v102, 16, v100
	v_mul_lo_u32 v102, v102, s58
	v_lshl_add_u32 v230, v101, 4, v102
	v_xor_b32_e32 v101, v104, v96
	v_xor_b32_e32 v101, 4, v101
	v_add_u32_e32 v102, 24, v100
	v_mul_lo_u32 v102, v102, s58
	v_lshl_add_u32 v231, v101, 4, v102
	v_and_b32_e32 v104, 3, v110
	v_xor_b32_e32 v101, v104, v96
	v_lshrrev_b32_e32 v100, 2, v110
	v_add_u32_e32 v102, 0, v100
	v_mul_lo_u32 v102, v102, s59
	v_lshl_add_u32 v232, v101, 4, v102
	v_add_u32_e32 v102, 16, v100
	v_mul_lo_u32 v102, v102, s59
	v_lshl_add_u32 v233, v101, 4, v102
	v_add_u32_e32 v102, 32, v100
	v_mul_lo_u32 v102, v102, s59
	v_lshl_add_u32 v234, v101, 4, v102
	v_add_u32_e32 v102, 48, v100
	v_mul_lo_u32 v102, v102, s59
	v_lshl_add_u32 v235, v101, 4, v102
	v_bfe_u32 v96, v108, 1, 3
	v_lshl_add_u32 v102, v108, 7, s70
	v_or_b32_e32 v101, 0, v109
	v_xor_b32_e32 v101, v101, v96
	v_lshl_add_u32 v236, v101, 4, v102
	v_or_b32_e32 v101, 2, v109
	v_xor_b32_e32 v101, v101, v96
	v_lshl_add_u32 v237, v101, 4, v102
	v_or_b32_e32 v101, 4, v109
	v_xor_b32_e32 v101, v101, v96
	v_lshl_add_u32 v238, v101, 4, v102
	v_or_b32_e32 v101, 6, v109
	v_xor_b32_e32 v101, v101, v96
	v_lshl_add_u32 v239, v101, 4, v102
	v_bfe_u32 v96, v108, 2, 2
	v_lshl_add_u32 v102, v108, 6, s70
	v_lshl_add_u32 v102, v109, 3, v102
	v_add_u32_e32 v102, 0x1000, v102
	v_xor_b32_e32 v101, 0, v96
	v_lshl_add_u32 v240, v101, 4, v102
	v_xor_b32_e32 v101, 1, v96
	v_lshl_add_u32 v241, v101, 4, v102
	v_xor_b32_e32 v101, 2, v96
	v_lshl_add_u32 v242, v101, 4, v102
	v_xor_b32_e32 v101, 3, v96
	v_lshl_add_u32 v243, v101, 4, v102
	v_lshlrev_b32_e32 v101, 2, v109
	v_sub_u32_e32 v101, v108, v101
	v_add_u32_e32 v101, 0x80, v101
	v_lshlrev_b32_e32 v244, 2, v101
	v_mul_lo_u32 v245, v108, s58
	v_lshl_add_u32 v245, v109, 3, v245
	s_lshl_b32 s75, s58, 5
	s_add_i32 s76, s67, 0x400
	s_mov_b32 s78, 0
	s_cmp_eq_u32 s68, 0
	s_cbranch_scc1 .Lat_nob_3
	v_mov_b32_e32 v110, s76
	ds_read_b32 v110, v110
	s_waitcnt lgkmcnt(0)
	s_nop 0
	v_readfirstlane_b32 s78, v110
; #define LAS __attribute__((address_space(3)))
; #define MFMA32(a, b, c) __builtin_amdgcn_mfma_f32_32x32x16_bf16((a), (b), (c), 0, 0, 0)
; #define ATT_LOAD(KR, VR, kb_) do { _Pragma("unroll") for (int i = 0; i < 4; ++i) { KR[i] = *(const u32x4*)(kg + (size_t)(32 * (kb_) + 8 * i) * it.kld); VR[i] = *(const u32x4*)(vg + (size_t)(16 * i) * it.vtld + 32 * (kb_)); } } while (0)
; #define ATT_STORE(KR, VR) do { _Pragma("unroll") for (int i = 0; i < 4; ++i) { *(LAS u32x4*)(Kl + kw + i * 1152) = KR[i]; *(LAS u32x4*)(Vl + vw + i * 1280) = VR[i]; } } while (0)
; DI void attn_block(const AttnItem& it, int key0, int qi, int hh, const bf16x8 (&bq)[4], LAS unsigned char* Kl, LAS unsigned char* Vl, unsigned kr, unsigned vr,
;                    float& mrun, float& lsum, f32x16& o0, f32x16& o1) {
;     ...
; #pragma unroll
;     for (int r = 0; r < 16; ++r) s[r] = 0.f;
; #pragma unroll
;     for (int kk = 0; kk < 4; ++kk) { const bf16x8 ak = *(const LAS bf16x8*)(Kl + kr + kk * 32); s = MFMA32(ak, bq[kk], s); }
; DI void attn_item(const AttnItem& it, LAS unsigned char* wl, int lane) {
;     ...
;     float mrun = -1e30f, lsum = 0.f;
;     f32x16 o0, o1;
; #pragma unroll
;     for (int r = 0; r < 16; ++r) { o0[r] = 0.f; o1[r] = 0.f; }
;     const int krow = lane >> 3, kch = lane & 7, vrow = lane >> 2, vch = lane & 3;
;     const bf16_t* kg = it.k + (size_t)krow * it.kld + 8 * kch;
;     const bf16_t* vg = it.vt + (size_t)vrow * it.vtld + 8 * vch;
;     LAS unsigned char* Kl = wl; LAS unsigned char* Vl = wl + 4608;
;     const unsigned kw = krow * 144 + kch * 16, vw = vrow * 80 + vch * 16;
;     const unsigned kr = qi * 144 + hh * 16, vr = qi * 80 + hh * 8;
;     u32x4 kA[4], vA[4], kB[4], vB[4];
;     ...
;     ATT_LOAD(kA, vA, 0);
;     if (it.nkb > 1) ATT_LOAD(kB, vB, 1);
;     for (int kb = 0; kb < it.nkb; kb += 2) {
;         ATT_STORE(kA, vA);
;         if (kb + 2 < it.nkb) ATT_LOAD(kA, vA, kb + 2);
;         attn_block(it, 32 * kb, qi, hh, bq, Kl, Vl, kr, vr, mrun, lsum, o0, o1);
.Lat_nob_3:
	v_mov_b32_e32 v107, 0xf149f2ca
	v_mov_b32_e32 v98, 0xf149f2ca
	v_mov_b32_e32 v99, 0
	v_mov_b32_e32 v16, 0
	v_mov_b32_e32 v17, 0
	v_mov_b32_e32 v18, 0
	v_mov_b32_e32 v19, 0
	v_mov_b32_e32 v20, 0
	v_mov_b32_e32 v21, 0
	v_mov_b32_e32 v22, 0
	v_mov_b32_e32 v23, 0
	v_mov_b32_e32 v24, 0
	v_mov_b32_e32 v25, 0
	v_mov_b32_e32 v26, 0
	v_mov_b32_e32 v27, 0
	v_mov_b32_e32 v28, 0
	v_mov_b32_e32 v29, 0
	v_mov_b32_e32 v30, 0
	v_mov_b32_e32 v31, 0
	v_mov_b32_e32 v32, 0
	v_mov_b32_e32 v33, 0
	v_mov_b32_e32 v34, 0
	v_mov_b32_e32 v35, 0
	v_mov_b32_e32 v36, 0
	v_mov_b32_e32 v37, 0
	v_mov_b32_e32 v38, 0
	v_mov_b32_e32 v39, 0
	v_mov_b32_e32 v40, 0
	v_mov_b32_e32 v41, 0
	v_mov_b32_e32 v42, 0
	v_mov_b32_e32 v43, 0
	v_mov_b32_e32 v44, 0
	v_mov_b32_e32 v45, 0
	v_mov_b32_e32 v46, 0
	v_mov_b32_e32 v47, 0
	s_mov_b32 s71, 0
	s_mov_b32 s72, 0
	s_add_i32 m0, s70, 0x0
	s_nop 0
	global_load_lds_dwordx4 v228, s[52:53]
	s_add_i32 m0, s70, 0x400
	s_nop 0
	global_load_lds_dwordx4 v229, s[52:53]
	s_add_i32 m0, s70, 0x800
	s_nop 0
	global_load_lds_dwordx4 v230, s[52:53]
	s_add_i32 m0, s70, 0xc00
	s_nop 0
	global_load_lds_dwordx4 v231, s[52:53]
	s_add_u32 s52, s52, s75
	s_addc_u32 s53, s53, 0
	s_add_i32 m0, s70, 0x1000
	s_nop 0
	global_load_lds_dwordx4 v232, s[54:55]
	s_add_i32 m0, s70, 0x1400
	s_nop 0
	global_load_lds_dwordx4 v233, s[54:55]
	s_add_i32 m0, s70, 0x1800
	s_nop 0
	global_load_lds_dwordx4 v234, s[54:55]
	s_add_i32 m0, s70, 0x1c00
	s_nop 0
	global_load_lds_dwordx4 v235, s[54:55]
	s_add_u32 s54, s54, s84
	s_addc_u32 s55, s55, 0
	s_add_i32 m0, s70, 0x2000
	s_nop 0
	global_load_lds_dwordx4 v228, s[52:53]
	s_add_i32 m0, s70, 0x2400
	s_nop 0
	global_load_lds_dwordx4 v229, s[52:53]
	s_add_i32 m0, s70, 0x2800
	s_nop 0
	global_load_lds_dwordx4 v230, s[52:53]
	s_add_i32 m0, s70, 0x2c00
	s_nop 0
	global_load_lds_dwordx4 v231, s[52:53]
	s_add_u32 s52, s52, s75
	s_addc_u32 s53, s53, 0
	s_add_i32 m0, s70, 0x3000
	s_nop 0
	global_load_lds_dwordx4 v232, s[54:55]
	s_add_i32 m0, s70, 0x3400
	s_nop 0
	global_load_lds_dwordx4 v233, s[54:55]
	s_add_i32 m0, s70, 0x3800
	s_nop 0
	global_load_lds_dwordx4 v234, s[54:55]
	s_add_i32 m0, s70, 0x3c00
	s_nop 0
	global_load_lds_dwordx4 v235, s[54:55]
	s_add_u32 s54, s54, s84
	s_addc_u32 s55, s55, 0
	s_waitcnt vmcnt(12)
	ds_read_b128 v[80:83], v236 offset:0
	ds_read_b128 v[84:87], v237 offset:0
	ds_read_b128 v[88:91], v238 offset:0
	ds_read_b128 v[92:95], v239 offset:0
	s_waitcnt lgkmcnt(0)
	v_mfma_f32_32x32x16_bf16 v[48:63], v[80:83], v[0:3], 0
	v_mfma_f32_32x32x16_bf16 v[48:63], v[84:87], v[4:7], v[48:63]
	v_mfma_f32_32x32x16_bf16 v[48:63], v[88:91], v[8:11], v[48:63]
	v_mfma_f32_32x32x16_bf16 v[48:63], v[92:95], v[12:15], v[48:63]
	s_nop 15
.Lat_loop:
	s_add_i32 s77, s71, 2
	s_cmp_lt_u32 s77, s65
	s_cbranch_scc0 .Lat_nodma_4
	s_add_i32 m0, s70, 0x0
	s_nop 0
	global_load_lds_dwordx4 v228, s[52:53]
	s_add_i32 m0, s70, 0x400
	s_nop 0
	global_load_lds_dwordx4 v229, s[52:53]
	s_add_i32 m0, s70, 0x800
	s_nop 0
	global_load_lds_dwordx4 v230, s[52:53]
	s_add_i32 m0, s70, 0xc00
	s_nop 0
	global_load_lds_dwordx4 v231, s[52:53]
	s_add_u32 s52, s52, s75
	s_addc_u32 s53, s53, 0
.Lat_nodma_4:
	s_add_i32 s79, s71, 1
	s_cmp_lt_u32 s79, s65
	s_cbranch_scc0 .Lat_last_7
	s_cmp_lt_u32 s77, s65
	s_cbranch_scc0 .Lat_w4_6
	s_waitcnt vmcnt(8)
	s_branch .Lat_w_5
.Lat_w4_6:
	s_waitcnt vmcnt(4)
.Lat_w_5:
	ds_read_b128 v[80:83], v236 offset:8192
	ds_read_b128 v[84:87], v237 offset:8192
	ds_read_b128 v[88:91], v238 offset:8192
	ds_read_b128 v[92:95], v239 offset:8192
	s_branch .Lat_sdone_8

; DI void attn_block(const AttnItem& it, int key0, int qi, int hh, const bf16x8 (&bq)[4], LAS unsigned char* Kl, LAS unsigned char* Vl, unsigned kr, unsigned vr,
;                    float& mrun, float& lsum, f32x16& o0, f32x16& o1) {
;     ...
;     if (it.bias) {
;         const int d0 = it.qpos0 - key0;
;         if (d0 - 31 >= 128) {
;             const float bc = it.bias[256];
; #pragma unroll
;             for (int r = 0; r < 16; ++r) s[r] += bc;
;         } else {
; #pragma unroll
;             for (int r = 0; r < 16; ++r) {
;                 int d = d0 + qi - ((r & 3) + 8 * (r >> 2) + 4 * hh);
;                 d = d < -128 ? -128 : (d > 128 ? 128 : d);
;                 s[r] += it.bias[d + 128];
;             }
;         }
;     }
;     if (key0 + 32 > it.nkeys) {
; #pragma unroll
;         for (int r = 0; r < 16; ++r) if (key0 + (r & 3) + 8 * (r >> 2) + 4 * hh >= it.nkeys) s[r] = -1e30f;
;     }
;     float mx = s[0];
; #pragma unroll
;     for (int r = 1; r < 16; ++r) mx = fmaxf(mx, s[r]);
;     mx = fmaxf(mx, __shfl_xor(mx, 32));
;     const float mnew = fmaxf(mrun, mx);
;     const float alpha = __builtin_amdgcn_exp2f(mrun - mnew);
;     mrun = mnew;
.Lat_sdone_8:
	s_cmpk_ge_i32 s66, 0x9f
	s_cbranch_scc1 .Lat_far_9
	s_lshl_b32 s82, s66, 2
	s_add_i32 s82, s82, s67
	v_add_u32_e32 v106, s82, v244
	v_min_u32_e32 v116, s76, v106
	v_subrev_u32_e32 v117, 4, v106
	v_min_u32_e32 v117, s76, v117
	v_subrev_u32_e32 v118, 8, v106
	v_min_u32_e32 v118, s76, v118
	v_subrev_u32_e32 v119, 12, v106
	v_min_u32_e32 v119, s76, v119
	v_subrev_u32_e32 v120, 32, v106
	v_min_u32_e32 v120, s76, v120
	v_subrev_u32_e32 v121, 36, v106
	v_min_u32_e32 v121, s76, v121
	v_subrev_u32_e32 v122, 40, v106
	v_min_u32_e32 v122, s76, v122
	v_subrev_u32_e32 v123, 44, v106
	v_min_u32_e32 v123, s76, v123
	v_subrev_u32_e32 v124, 64, v106
	v_min_u32_e32 v124, s76, v124
	v_subrev_u32_e32 v125, 68, v106
	v_min_u32_e32 v125, s76, v125
	v_subrev_u32_e32 v126, 72, v106
	v_min_u32_e32 v126, s76, v126
	v_subrev_u32_e32 v127, 76, v106
	v_min_u32_e32 v127, s76, v127
	v_subrev_u32_e32 v157, 96, v106
	v_min_u32_e32 v157, s76, v157
	v_subrev_u32_e32 v158, 100, v106
	v_min_u32_e32 v158, s76, v158
	v_subrev_u32_e32 v159, 104, v106
	v_min_u32_e32 v159, s76, v159
	v_subrev_u32_e32 v160, 108, v106
	v_min_u32_e32 v160, s76, v160
	ds_read_b32 v116, v116
	ds_read_b32 v117, v117
	ds_read_b32 v118, v118
	ds_read_b32 v119, v119
	ds_read_b32 v120, v120
	ds_read_b32 v121, v121
	ds_read_b32 v122, v122
	ds_read_b32 v123, v123
	ds_read_b32 v124, v124
	ds_read_b32 v125, v125
	ds_read_b32 v126, v126
	ds_read_b32 v127, v127
	ds_read_b32 v157, v157
	ds_read_b32 v158, v158
	ds_read_b32 v159, v159
	ds_read_b32 v160, v160
	s_waitcnt lgkmcnt(0)
	v_add_f32_e32 v48, v48, v116
	v_add_f32_e32 v49, v49, v117
	v_add_f32_e32 v50, v50, v118
	v_add_f32_e32 v51, v51, v119
	v_add_f32_e32 v52, v52, v120
	v_add_f32_e32 v53, v53, v121
	v_add_f32_e32 v54, v54, v122
	v_add_f32_e32 v55, v55, v123
	v_add_f32_e32 v56, v56, v124
	v_add_f32_e32 v57, v57, v125
	v_add_f32_e32 v58, v58, v126
	v_add_f32_e32 v59, v59, v127
	v_add_f32_e32 v60, v60, v157
	v_add_f32_e32 v61, v61, v158
	v_add_f32_e32 v62, v62, v159
	v_add_f32_e32 v63, v63, v160
	s_mov_b32 s83, 0
	s_branch .Lat_bdone_10
.Lat_far_9:
	s_mov_b32 s83, s78
.Lat_bdone_10:
	s_add_i32 s82, s72, 32
	s_cmp_le_u32 s82, s64
	s_cbranch_scc1 .Lat_nomask_11
	v_lshl_add_u32 v105, v109, 2, s72
	v_add_u32_e32 v110, 0, v105
	v_cmp_gt_u32_e32 vcc, s64, v110
	s_nop 1
	v_cndmask_b32_e32 v48, v107, v48, vcc
	v_add_u32_e32 v110, 1, v105
	v_cmp_gt_u32_e32 vcc, s64, v110
	s_nop 1
	v_cndmask_b32_e32 v49, v107, v49, vcc
	v_add_u32_e32 v110, 2, v105
	v_cmp_gt_u32_e32 vcc, s64, v110
	s_nop 1
	v_cndmask_b32_e32 v50, v107, v50, vcc
	v_add_u32_e32 v110, 3, v105
	v_cmp_gt_u32_e32 vcc, s64, v110
	s_nop 1
	v_cndmask_b32_e32 v51, v107, v51, vcc
	v_add_u32_e32 v110, 8, v105
	v_cmp_gt_u32_e32 vcc, s64, v110
	s_nop 1
	v_cndmask_b32_e32 v52, v107, v52, vcc
	v_add_u32_e32 v110, 9, v105
	v_cmp_gt_u32_e32 vcc, s64, v110
	s_nop 1
	v_cndmask_b32_e32 v53, v107, v53, vcc
	v_add_u32_e32 v110, 10, v105
	v_cmp_gt_u32_e32 vcc, s64, v110
	s_nop 1
	v_cndmask_b32_e32 v54, v107, v54, vcc
	v_add_u32_e32 v110, 11, v105
	v_cmp_gt_u32_e32 vcc, s64, v110
	s_nop 1
	v_cndmask_b32_e32 v55, v107, v55, vcc
	v_add_u32_e32 v110, 16, v105
	v_cmp_gt_u32_e32 vcc, s64, v110
	s_nop 1
	v_cndmask_b32_e32 v56, v107, v56, vcc
	v_add_u32_e32 v110, 17, v105
	v_cmp_gt_u32_e32 vcc, s64, v110
	s_nop 1
	v_cndmask_b32_e32 v57, v107, v57, vcc
	v_add_u32_e32 v110, 18, v105
	v_cmp_gt_u32_e32 vcc, s64, v110
	s_nop 1
	v_cndmask_b32_e32 v58, v107, v58, vcc
	v_add_u32_e32 v110, 19, v105
	v_cmp_gt_u32_e32 vcc, s64, v110
	s_nop 1
	v_cndmask_b32_e32 v59, v107, v59, vcc
	v_add_u32_e32 v110, 24, v105
	v_cmp_gt_u32_e32 vcc, s64, v110
	s_nop 1
	v_cndmask_b32_e32 v60, v107, v60, vcc
	v_add_u32_e32 v110, 25, v105
	v_cmp_gt_u32_e32 vcc, s64, v110
	s_nop 1
	v_cndmask_b32_e32 v61, v107, v61, vcc
	v_add_u32_e32 v110, 26, v105
	v_cmp_gt_u32_e32 vcc, s64, v110
	s_nop 1
	v_cndmask_b32_e32 v62, v107, v62, vcc
	v_add_u32_e32 v110, 27, v105
	v_cmp_gt_u32_e32 vcc, s64, v110
	s_nop 1
	v_cndmask_b32_e32 v63, v107, v63, vcc
.Lat_nomask_11:
	v_max3_f32 v96, v48, v49, v50
	v_max3_f32 v97, v51, v52, v53
	v_max3_f32 v96, v96, v54, v55
	v_max3_f32 v97, v97, v56, v57
	v_max3_f32 v96, v96, v58, v59
	v_max3_f32 v97, v97, v60, v61
	v_max3_f32 v96, v96, v62, v63
	v_max_f32_e32 v96, v96, v97
	v_mov_b32_e32 v97, v96
	s_nop 1
	v_permlane32_swap_b32_e32 v96, v97
	v_max_f32_e32 v96, v96, v97
	v_add_f32_e32 v96, s83, v96
	v_max_f32_e32 v96, v98, v96
	v_sub_f32_e32 v100, v98, v96
	v_exp_f32_e32 v100, v100
	v_sub_f32_e32 v101, s83, v96
	v_mov_b32_e32 v98, v96
	s_cmp_lt_u32 s79, s65
	s_cbranch_scc0 .Lat_nomfma_13
	s_waitcnt lgkmcnt(0)
	v_mfma_f32_32x32x16_bf16 v[64:79], v[80:83], v[0:3], 0
	v_mfma_f32_32x32x16_bf16 v[64:79], v[84:87], v[4:7], v[64:79]
	v_mfma_f32_32x32x16_bf16 v[64:79], v[88:91], v[8:11], v[64:79]
	v_mfma_f32_32x32x16_bf16 v[64:79], v[92:95], v[12:15], v[64:79]
; #define LAS __attribute__((address_space(3)))
; DI unsigned pk2(float a, float b) { f32x2 v = {a, b}; bf2v r = __builtin_convertvector(v, bf2v); return __builtin_bit_cast(unsigned, r); }
; #define MFMA32(a, b, c) __builtin_amdgcn_mfma_f32_32x32x16_bf16((a), (b), (c), 0, 0, 0)
; DI void attn_block(const AttnItem& it, int key0, int qi, int hh, const bf16x8 (&bq)[4], LAS unsigned char* Kl, LAS unsigned char* Vl, unsigned kr, unsigned vr,
;                    float& mrun, float& lsum, f32x16& o0, f32x16& o1) {
;     ...
;     float rs = 0.f;
; #pragma unroll
;     for (int r = 0; r < 16; ++r) { s[r] = __builtin_amdgcn_exp2f(s[r] - mnew); rs += s[r]; }
;     lsum = lsum * alpha + rs;
; #pragma unroll
;     for (int r = 0; r < 16; ++r) { o0[r] *= alpha; o1[r] *= alpha; }
; #pragma unroll
;     for (int ks = 0; ks < 2; ++ks) {
;         u32x4 pw; pw.x = pk2(s[8 * ks], s[8 * ks + 1]); pw.y = pk2(s[8 * ks + 2], s[8 * ks + 3]); pw.z = pk2(s[8 * ks + 4], s[8 * ks + 5]); pw.w = pk2(s[8 * ks + 6], s[8 * ks + 7]);
;         const bf16x8 pb = __builtin_bit_cast(bf16x8, pw);
;         const u32x2 a00 = *(const LAS u32x2*)(Vl + vr + ks * 32), a01 = *(const LAS u32x2*)(Vl + vr + ks * 32 + 16);
;         const u32x2 a10 = *(const LAS u32x2*)(Vl + vr + 2560 + ks * 32), a11 = *(const LAS u32x2*)(Vl + vr + 2560 + ks * 32 + 16);
;         u32x4 a0; a0.x = a00.x; a0.y = a00.y; a0.z = a01.x; a0.w = a01.y;
;         u32x4 a1; a1.x = a10.x; a1.y = a10.y; a1.z = a11.x; a1.w = a11.y;
;         o0 = MFMA32(__builtin_bit_cast(bf16x8, a0), pb, o0);
;         o1 = MFMA32(__builtin_bit_cast(bf16x8, a1), pb, o1);
;     }
.Lat_nomfma_13:
	v_add_f32_e32 v48, v101, v48
	v_add_f32_e32 v49, v101, v49
	v_add_f32_e32 v50, v101, v50
	v_add_f32_e32 v51, v101, v51
	v_add_f32_e32 v52, v101, v52
	v_add_f32_e32 v53, v101, v53
	v_add_f32_e32 v54, v101, v54
	v_add_f32_e32 v55, v101, v55
	v_add_f32_e32 v56, v101, v56
	v_add_f32_e32 v57, v101, v57
	v_add_f32_e32 v58, v101, v58
	v_add_f32_e32 v59, v101, v59
	v_add_f32_e32 v60, v101, v60
	v_add_f32_e32 v61, v101, v61
	v_add_f32_e32 v62, v101, v62
	v_add_f32_e32 v63, v101, v63
	v_exp_f32_e32 v48, v48
	v_exp_f32_e32 v49, v49
	v_exp_f32_e32 v50, v50
	v_exp_f32_e32 v51, v51
	v_exp_f32_e32 v52, v52
	v_exp_f32_e32 v53, v53
	v_exp_f32_e32 v54, v54
	v_exp_f32_e32 v55, v55
	v_exp_f32_e32 v56, v56
	v_exp_f32_e32 v57, v57
	v_exp_f32_e32 v58, v58
	v_exp_f32_e32 v59, v59
	v_exp_f32_e32 v60, v60
	v_exp_f32_e32 v61, v61
	v_exp_f32_e32 v62, v62
	v_exp_f32_e32 v63, v63
	v_add_f32_e32 v102, v48, v49
	v_add_f32_e32 v103, v50, v51
	v_add_f32_e32 v102, v102, v52
	v_add_f32_e32 v103, v103, v53
	v_add_f32_e32 v102, v102, v54
	v_add_f32_e32 v103, v103, v55
	v_add_f32_e32 v102, v102, v56
	v_add_f32_e32 v103, v103, v57
	v_add_f32_e32 v102, v102, v58
	v_add_f32_e32 v103, v103, v59
	v_add_f32_e32 v102, v102, v60
	v_add_f32_e32 v103, v103, v61
	v_add_f32_e32 v102, v102, v62
	v_add_f32_e32 v103, v103, v63
	v_add_f32_e32 v102, v102, v103
	v_fma_f32 v99, v99, v100, v102
	ds_read_b64 v[212:213], v240 offset:0
	ds_read_b64 v[214:215], v241 offset:0
	ds_read_b64 v[216:217], v240 offset:2048
	ds_read_b64 v[218:219], v241 offset:2048
	ds_read_b64 v[220:221], v242 offset:0
	ds_read_b64 v[222:223], v243 offset:0
	ds_read_b64 v[224:225], v242 offset:2048
	ds_read_b64 v[226:227], v243 offset:2048
	v_mul_f32_e32 v16, v100, v16
	v_mul_f32_e32 v32, v100, v32
	v_mul_f32_e32 v17, v100, v17
	v_mul_f32_e32 v33, v100, v33
	v_mul_f32_e32 v18, v100, v18
	v_mul_f32_e32 v34, v100, v34
	v_mul_f32_e32 v19, v100, v19
	v_mul_f32_e32 v35, v100, v35
	v_mul_f32_e32 v20, v100, v20
	v_mul_f32_e32 v36, v100, v36
	v_mul_f32_e32 v21, v100, v21
	v_mul_f32_e32 v37, v100, v37
	v_mul_f32_e32 v22, v100, v22
	v_mul_f32_e32 v38, v100, v38
	v_mul_f32_e32 v23, v100, v23
	v_mul_f32_e32 v39, v100, v39
	v_mul_f32_e32 v24, v100, v24
	v_mul_f32_e32 v40, v100, v40
	v_mul_f32_e32 v25, v100, v25
	v_mul_f32_e32 v41, v100, v41
	v_mul_f32_e32 v26, v100, v26
	v_mul_f32_e32 v42, v100, v42
	v_mul_f32_e32 v27, v100, v27
	v_mul_f32_e32 v43, v100, v43
	v_mul_f32_e32 v28, v100, v28
	v_mul_f32_e32 v44, v100, v44
	v_mul_f32_e32 v29, v100, v29
	v_mul_f32_e32 v45, v100, v45
	v_mul_f32_e32 v30, v100, v30
	v_mul_f32_e32 v46, v100, v46
	v_mul_f32_e32 v31, v100, v31
	v_mul_f32_e32 v47, v100, v47
	v_cvt_pk_bf16_f32 v48, v48, v49
	v_cvt_pk_bf16_f32 v49, v50, v51
	v_cvt_pk_bf16_f32 v50, v52, v53
	v_cvt_pk_bf16_f32 v51, v54, v55
	v_cvt_pk_bf16_f32 v56, v56, v57
	v_cvt_pk_bf16_f32 v57, v58, v59
	v_cvt_pk_bf16_f32 v58, v60, v61
	v_cvt_pk_bf16_f32 v59, v62, v63
	s_waitcnt lgkmcnt(0)
	s_cmp_lt_u32 s77, s65
	s_cbranch_scc0 .Lat_novdma_12
	s_add_i32 m0, s70, 0x1000
	s_nop 0
	global_load_lds_dwordx4 v232, s[54:55]
	s_add_i32 m0, s70, 0x1400
	s_nop 0
	global_load_lds_dwordx4 v233, s[54:55]
	s_add_i32 m0, s70, 0x1800
	s_nop 0
	global_load_lds_dwordx4 v234, s[54:55]
	s_add_i32 m0, s70, 0x1c00
	s_nop 0
	global_load_lds_dwordx4 v235, s[54:55]
	s_add_u32 s54, s54, s84
	s_addc_u32 s55, s55, 0
.Lat_novdma_12:
	v_mfma_f32_32x32x16_bf16 v[16:31], v[212:215], v[48:51], v[16:31]
	v_mfma_f32_32x32x16_bf16 v[32:47], v[216:219], v[48:51], v[32:47]
	v_mfma_f32_32x32x16_bf16 v[16:31], v[220:223], v[56:59], v[16:31]
	v_mfma_f32_32x32x16_bf16 v[32:47], v[224:227], v[56:59], v[32:47]
	s_add_i32 s71, s71, 1
	s_add_i32 s72, s72, 32
	s_sub_i32 s66, s66, 32
	s_cmp_lt_u32 s71, s65
	s_cbranch_scc0 .Lat_done
	s_add_i32 s77, s71, 2
	s_cmp_lt_u32 s77, s65
	s_cbranch_scc0 .Lat_nodma_14
	s_add_i32 m0, s70, 0x2000
	s_nop 0
	global_load_lds_dwordx4 v228, s[52:53]
	s_add_i32 m0, s70, 0x2400
	s_nop 0
	global_load_lds_dwordx4 v229, s[52:53]
	s_add_i32 m0, s70, 0x2800
	s_nop 0
	global_load_lds_dwordx4 v230, s[52:53]
	s_add_i32 m0, s70, 0x2c00
	s_nop 0
	global_load_lds_dwordx4 v231, s[52:53]
	s_add_u32 s52, s52, s75
	s_addc_u32 s53, s53, 0

; #define ATT_LOAD(KR, VR, kb_) do { _Pragma("unroll") for (int i = 0; i < 4; ++i) { KR[i] = *(const u32x4*)(kg + (size_t)(32 * (kb_) + 8 * i) * it.kld); VR[i] = *(const u32x4*)(vg + (size_t)(16 * i) * it.vtld + 32 * (kb_)); } } while (0)
; #define ATT_STORE(KR, VR) do { _Pragma("unroll") for (int i = 0; i < 4; ++i) { *(LAS u32x4*)(Kl + kw + i * 1152) = KR[i]; *(LAS u32x4*)(Vl + vw + i * 1280) = VR[i]; } } while (0)
; DI void attn_item(const AttnItem& it, LAS unsigned char* wl, int lane) {
;     ...
;     for (int kb = 0; kb < it.nkb; kb += 2) {
;         ATT_STORE(kA, vA);
;         if (kb + 2 < it.nkb) ATT_LOAD(kA, vA, kb + 2);
;         attn_block(it, 32 * kb, qi, hh, bq, Kl, Vl, kr, vr, mrun, lsum, o0, o1);
;         if (kb + 1 < it.nkb) {
;             ATT_STORE(kB, vB);
;             if (kb + 3 < it.nkb) ATT_LOAD(kB, vB, kb + 3);
;             attn_block(it, 32 * kb + 32, qi, hh, bq, Kl, Vl, kr, vr, mrun, lsum, o0, o1);
.Lat_w_15:
	ds_read_b128 v[80:83], v236 offset:0
	ds_read_b128 v[84:87], v237 offset:0
	ds_read_b128 v[88:91], v238 offset:0
	ds_read_b128 v[92:95], v239 offset:0
	s_branch .Lat_sdone_18

; DI void attn_block(const AttnItem& it, int key0, int qi, int hh, const bf16x8 (&bq)[4], LAS unsigned char* Kl, LAS unsigned char* Vl, unsigned kr, unsigned vr,
;                    float& mrun, float& lsum, f32x16& o0, f32x16& o1) {
;     ...
;     if (it.bias) {
;         const int d0 = it.qpos0 - key0;
;         if (d0 - 31 >= 128) {
;             const float bc = it.bias[256];
; #pragma unroll
;             for (int r = 0; r < 16; ++r) s[r] += bc;
;         } else {
; #pragma unroll
;             for (int r = 0; r < 16; ++r) {
;                 int d = d0 + qi - ((r & 3) + 8 * (r >> 2) + 4 * hh);
;                 d = d < -128 ? -128 : (d > 128 ? 128 : d);
;                 s[r] += it.bias[d + 128];
;             }
;         }
;     }
.Lat_sdone_18:
	s_cmpk_ge_i32 s66, 0x9f
	s_cbranch_scc1 .Lat_far_19
	s_lshl_b32 s82, s66, 2
	s_add_i32 s82, s82, s67
	v_add_u32_e32 v106, s82, v244
	v_min_u32_e32 v116, s76, v106
	v_subrev_u32_e32 v117, 4, v106
	v_min_u32_e32 v117, s76, v117
	v_subrev_u32_e32 v118, 8, v106
	v_min_u32_e32 v118, s76, v118
	v_subrev_u32_e32 v119, 12, v106
	v_min_u32_e32 v119, s76, v119
	v_subrev_u32_e32 v120, 32, v106
	v_min_u32_e32 v120, s76, v120
	v_subrev_u32_e32 v121, 36, v106
	v_min_u32_e32 v121, s76, v121
	v_subrev_u32_e32 v122, 40, v106
	v_min_u32_e32 v122, s76, v122
	v_subrev_u32_e32 v123, 44, v106
	v_min_u32_e32 v123, s76, v123
	v_subrev_u32_e32 v124, 64, v106
	v_min_u32_e32 v124, s76, v124
	v_subrev_u32_e32 v125, 68, v106
	v_min_u32_e32 v125, s76, v125
	v_subrev_u32_e32 v126, 72, v106
	v_min_u32_e32 v126, s76, v126
	v_subrev_u32_e32 v127, 76, v106
	v_min_u32_e32 v127, s76, v127
	v_subrev_u32_e32 v157, 96, v106
	v_min_u32_e32 v157, s76, v157
	v_subrev_u32_e32 v158, 100, v106
	v_min_u32_e32 v158, s76, v158
	v_subrev_u32_e32 v159, 104, v106
	v_min_u32_e32 v159, s76, v159
	v_subrev_u32_e32 v160, 108, v106
	v_min_u32_e32 v160, s76, v160
	ds_read_b32 v116, v116
	ds_read_b32 v117, v117
	ds_read_b32 v118, v118
	ds_read_b32 v119, v119
	ds_read_b32 v120, v120
	ds_read_b32 v121, v121
	ds_read_b32 v122, v122
	ds_read_b32 v123, v123
	ds_read_b32 v124, v124
	ds_read_b32 v125, v125
	ds_read_b32 v126, v126
	ds_read_b32 v127, v127
	ds_read_b32 v157, v157
	ds_read_b32 v158, v158
	ds_read_b32 v159, v159
	ds_read_b32 v160, v160
	s_waitcnt lgkmcnt(0)
	v_add_f32_e32 v64, v64, v116
	v_add_f32_e32 v65, v65, v117
	v_add_f32_e32 v66, v66, v118
	v_add_f32_e32 v67, v67, v119
	v_add_f32_e32 v68, v68, v120
	v_add_f32_e32 v69, v69, v121
	v_add_f32_e32 v70, v70, v122
	v_add_f32_e32 v71, v71, v123
	v_add_f32_e32 v72, v72, v124
	v_add_f32_e32 v73, v73, v125
	v_add_f32_e32 v74, v74, v126
	v_add_f32_e32 v75, v75, v127
	v_add_f32_e32 v76, v76, v157
	v_add_f32_e32 v77, v77, v158
	v_add_f32_e32 v78, v78, v159
	v_add_f32_e32 v79, v79, v160
	s_mov_b32 s83, 0
	s_branch .Lat_bdone_20

; #define LAS __attribute__((address_space(3)))
; DI unsigned pk2(float a, float b) { f32x2 v = {a, b}; bf2v r = __builtin_convertvector(v, bf2v); return __builtin_bit_cast(unsigned, r); }
; #define MFMA32(a, b, c) __builtin_amdgcn_mfma_f32_32x32x16_bf16((a), (b), (c), 0, 0, 0)
; DI void attn_block(const AttnItem& it, int key0, int qi, int hh, const bf16x8 (&bq)[4], LAS unsigned char* Kl, LAS unsigned char* Vl, unsigned kr, unsigned vr,
;                    float& mrun, float& lsum, f32x16& o0, f32x16& o1) {
;     ...
;     if (key0 + 32 > it.nkeys) {
; #pragma unroll
;         for (int r = 0; r < 16; ++r) if (key0 + (r & 3) + 8 * (r >> 2) + 4 * hh >= it.nkeys) s[r] = -1e30f;
;     }
;     float mx = s[0];
; #pragma unroll
;     for (int r = 1; r < 16; ++r) mx = fmaxf(mx, s[r]);
;     mx = fmaxf(mx, __shfl_xor(mx, 32));
;     const float mnew = fmaxf(mrun, mx);
;     const float alpha = __builtin_amdgcn_exp2f(mrun - mnew);
;     mrun = mnew;
;     float rs = 0.f;
; #pragma unroll
;     for (int r = 0; r < 16; ++r) { s[r] = __builtin_amdgcn_exp2f(s[r] - mnew); rs += s[r]; }
;     lsum = lsum * alpha + rs;
; #pragma unroll
;     for (int r = 0; r < 16; ++r) { o0[r] *= alpha; o1[r] *= alpha; }
; #pragma unroll
;     for (int ks = 0; ks < 2; ++ks) {
;         u32x4 pw; pw.x = pk2(s[8 * ks], s[8 * ks + 1]); pw.y = pk2(s[8 * ks + 2], s[8 * ks + 3]); pw.z = pk2(s[8 * ks + 4], s[8 * ks + 5]); pw.w = pk2(s[8 * ks + 6], s[8 * ks + 7]);
;         const bf16x8 pb = __builtin_bit_cast(bf16x8, pw);
;         const u32x2 a00 = *(const LAS u32x2*)(Vl + vr + ks * 32), a01 = *(const LAS u32x2*)(Vl + vr + ks * 32 + 16);
;         const u32x2 a10 = *(const LAS u32x2*)(Vl + vr + 2560 + ks * 32), a11 = *(const LAS u32x2*)(Vl + vr + 2560 + ks * 32 + 16);
;         u32x4 a0; a0.x = a00.x; a0.y = a00.y; a0.z = a01.x; a0.w = a01.y;
;         u32x4 a1; a1.x = a10.x; a1.y = a10.y; a1.z = a11.x; a1.w = a11.y;
;         o0 = MFMA32(__builtin_bit_cast(bf16x8, a0), pb, o0);
;         o1 = MFMA32(__builtin_bit_cast(bf16x8, a1), pb, o1);
;     }
.Lat_bdone_20:
	s_add_i32 s82, s72, 32
	s_cmp_le_u32 s82, s64
	s_cbranch_scc1 .Lat_nomask_21
	v_lshl_add_u32 v105, v109, 2, s72
	v_add_u32_e32 v110, 0, v105
	v_cmp_gt_u32_e32 vcc, s64, v110
	s_nop 1
	v_cndmask_b32_e32 v64, v107, v64, vcc
	v_add_u32_e32 v110, 1, v105
	v_cmp_gt_u32_e32 vcc, s64, v110
	s_nop 1
	v_cndmask_b32_e32 v65, v107, v65, vcc
	v_add_u32_e32 v110, 2, v105
	v_cmp_gt_u32_e32 vcc, s64, v110
	s_nop 1
	v_cndmask_b32_e32 v66, v107, v66, vcc
	v_add_u32_e32 v110, 3, v105
	v_cmp_gt_u32_e32 vcc, s64, v110
	s_nop 1
	v_cndmask_b32_e32 v67, v107, v67, vcc
	v_add_u32_e32 v110, 8, v105
	v_cmp_gt_u32_e32 vcc, s64, v110
	s_nop 1
	v_cndmask_b32_e32 v68, v107, v68, vcc
	v_add_u32_e32 v110, 9, v105
	v_cmp_gt_u32_e32 vcc, s64, v110
	s_nop 1
	v_cndmask_b32_e32 v69, v107, v69, vcc
	v_add_u32_e32 v110, 10, v105
	v_cmp_gt_u32_e32 vcc, s64, v110
	s_nop 1
	v_cndmask_b32_e32 v70, v107, v70, vcc
	v_add_u32_e32 v110, 11, v105
	v_cmp_gt_u32_e32 vcc, s64, v110
	s_nop 1
	v_cndmask_b32_e32 v71, v107, v71, vcc
	v_add_u32_e32 v110, 16, v105
	v_cmp_gt_u32_e32 vcc, s64, v110
	s_nop 1
	v_cndmask_b32_e32 v72, v107, v72, vcc
	v_add_u32_e32 v110, 17, v105
	v_cmp_gt_u32_e32 vcc, s64, v110
	s_nop 1
	v_cndmask_b32_e32 v73, v107, v73, vcc
	v_add_u32_e32 v110, 18, v105
	v_cmp_gt_u32_e32 vcc, s64, v110
	s_nop 1
	v_cndmask_b32_e32 v74, v107, v74, vcc
	v_add_u32_e32 v110, 19, v105
	v_cmp_gt_u32_e32 vcc, s64, v110
	s_nop 1
	v_cndmask_b32_e32 v75, v107, v75, vcc
	v_add_u32_e32 v110, 24, v105
	v_cmp_gt_u32_e32 vcc, s64, v110
	s_nop 1
	v_cndmask_b32_e32 v76, v107, v76, vcc
	v_add_u32_e32 v110, 25, v105
	v_cmp_gt_u32_e32 vcc, s64, v110
	s_nop 1
	v_cndmask_b32_e32 v77, v107, v77, vcc
	v_add_u32_e32 v110, 26, v105
	v_cmp_gt_u32_e32 vcc, s64, v110
	s_nop 1
	v_cndmask_b32_e32 v78, v107, v78, vcc
	v_add_u32_e32 v110, 27, v105
	v_cmp_gt_u32_e32 vcc, s64, v110
	s_nop 1
	v_cndmask_b32_e32 v79, v107, v79, vcc
.Lat_nomask_21:
	v_max3_f32 v96, v64, v65, v66
	v_max3_f32 v97, v67, v68, v69
	v_max3_f32 v96, v96, v70, v71
	v_max3_f32 v97, v97, v72, v73
	v_max3_f32 v96, v96, v74, v75
	v_max3_f32 v97, v97, v76, v77
	v_max3_f32 v96, v96, v78, v79
	v_max_f32_e32 v96, v96, v97
	v_mov_b32_e32 v97, v96
	s_nop 1
	v_permlane32_swap_b32_e32 v96, v97
	v_max_f32_e32 v96, v96, v97
	v_add_f32_e32 v96, s83, v96
	v_max_f32_e32 v96, v98, v96
	v_sub_f32_e32 v100, v98, v96
	v_exp_f32_e32 v100, v100
	v_sub_f32_e32 v101, s83, v96
	v_mov_b32_e32 v98, v96
	s_cmp_lt_u32 s79, s65
	s_cbranch_scc0 .Lat_nomfma_23
	s_waitcnt lgkmcnt(0)
	v_mfma_f32_32x32x16_bf16 v[48:63], v[80:83], v[0:3], 0
	v_mfma_f32_32x32x16_bf16 v[48:63], v[84:87], v[4:7], v[48:63]
	v_mfma_f32_32x32x16_bf16 v[48:63], v[88:91], v[8:11], v[48:63]
	v_mfma_f32_32x32x16_bf16 v[48:63], v[92:95], v[12:15], v[48:63]
.Lat_nomfma_23:
	v_add_f32_e32 v64, v101, v64
	v_add_f32_e32 v65, v101, v65
	v_add_f32_e32 v66, v101, v66
	v_add_f32_e32 v67, v101, v67
	v_add_f32_e32 v68, v101, v68
	v_add_f32_e32 v69, v101, v69
	v_add_f32_e32 v70, v101, v70
	v_add_f32_e32 v71, v101, v71
	v_add_f32_e32 v72, v101, v72
	v_add_f32_e32 v73, v101, v73
	v_add_f32_e32 v74, v101, v74
	v_add_f32_e32 v75, v101, v75
	v_add_f32_e32 v76, v101, v76
	v_add_f32_e32 v77, v101, v77
	v_add_f32_e32 v78, v101, v78
	v_add_f32_e32 v79, v101, v79
	v_exp_f32_e32 v64, v64
	v_exp_f32_e32 v65, v65
	v_exp_f32_e32 v66, v66
	v_exp_f32_e32 v67, v67
	v_exp_f32_e32 v68, v68
	v_exp_f32_e32 v69, v69
	v_exp_f32_e32 v70, v70
	v_exp_f32_e32 v71, v71
	v_exp_f32_e32 v72, v72
	v_exp_f32_e32 v73, v73
	v_exp_f32_e32 v74, v74
	v_exp_f32_e32 v75, v75
	v_exp_f32_e32 v76, v76
	v_exp_f32_e32 v77, v77
	v_exp_f32_e32 v78, v78
	v_exp_f32_e32 v79, v79
	v_add_f32_e32 v102, v64, v65
	v_add_f32_e32 v103, v66, v67
	v_add_f32_e32 v102, v102, v68
	v_add_f32_e32 v103, v103, v69
	v_add_f32_e32 v102, v102, v70
	v_add_f32_e32 v103, v103, v71
	v_add_f32_e32 v102, v102, v72
	v_add_f32_e32 v103, v103, v73
	v_add_f32_e32 v102, v102, v74
	v_add_f32_e32 v103, v103, v75
	v_add_f32_e32 v102, v102, v76
	v_add_f32_e32 v103, v103, v77
	v_add_f32_e32 v102, v102, v78
	v_add_f32_e32 v103, v103, v79
	v_add_f32_e32 v102, v102, v103
	v_fma_f32 v99, v99, v100, v102
	ds_read_b64 v[212:213], v240 offset:8192
	ds_read_b64 v[214:215], v241 offset:8192
	ds_read_b64 v[216:217], v240 offset:10240
	ds_read_b64 v[218:219], v241 offset:10240
	ds_read_b64 v[220:221], v242 offset:8192
	ds_read_b64 v[222:223], v243 offset:8192
	ds_read_b64 v[224:225], v242 offset:10240
	ds_read_b64 v[226:227], v243 offset:10240
	v_mul_f32_e32 v16, v100, v16
	v_mul_f32_e32 v32, v100, v32
	v_mul_f32_e32 v17, v100, v17
	v_mul_f32_e32 v33, v100, v33
	v_mul_f32_e32 v18, v100, v18
	v_mul_f32_e32 v34, v100, v34
	v_mul_f32_e32 v19, v100, v19
	v_mul_f32_e32 v35, v100, v35
	v_mul_f32_e32 v20, v100, v20
	v_mul_f32_e32 v36, v100, v36
	v_mul_f32_e32 v21, v100, v21
	v_mul_f32_e32 v37, v100, v37
	v_mul_f32_e32 v22, v100, v22
	v_mul_f32_e32 v38, v100, v38
	v_mul_f32_e32 v23, v100, v23
	v_mul_f32_e32 v39, v100, v39
	v_mul_f32_e32 v24, v100, v24
	v_mul_f32_e32 v40, v100, v40
	v_mul_f32_e32 v25, v100, v25
	v_mul_f32_e32 v41, v100, v41
	v_mul_f32_e32 v26, v100, v26
	v_mul_f32_e32 v42, v100, v42
	v_mul_f32_e32 v27, v100, v27
	v_mul_f32_e32 v43, v100, v43
	v_mul_f32_e32 v28, v100, v28
	v_mul_f32_e32 v44, v100, v44
	v_mul_f32_e32 v29, v100, v29
	v_mul_f32_e32 v45, v100, v45
	v_mul_f32_e32 v30, v100, v30
	v_mul_f32_e32 v46, v100, v46
	v_mul_f32_e32 v31, v100, v31
	v_mul_f32_e32 v47, v100, v47
	v_cvt_pk_bf16_f32 v64, v64, v65
	v_cvt_pk_bf16_f32 v65, v66, v67
	v_cvt_pk_bf16_f32 v66, v68, v69
	v_cvt_pk_bf16_f32 v67, v70, v71
	v_cvt_pk_bf16_f32 v72, v72, v73
	v_cvt_pk_bf16_f32 v73, v74, v75
	v_cvt_pk_bf16_f32 v74, v76, v77
	v_cvt_pk_bf16_f32 v75, v78, v79
	s_waitcnt lgkmcnt(0)
	s_cmp_lt_u32 s77, s65
	s_cbranch_scc0 .Lat_novdma_22
	s_add_i32 m0, s70, 0x3000
	s_nop 0
	global_load_lds_dwordx4 v232, s[54:55]
	s_add_i32 m0, s70, 0x3400
	s_nop 0
	global_load_lds_dwordx4 v233, s[54:55]
	s_add_i32 m0, s70, 0x3800
	s_nop 0
	global_load_lds_dwordx4 v234, s[54:55]
	s_add_i32 m0, s70, 0x3c00
	s_nop 0
	global_load_lds_dwordx4 v235, s[54:55]
	s_add_u32 s54, s54, s84
	s_addc_u32 s55, s55, 0
; DI unsigned pk2(float a, float b) { f32x2 v = {a, b}; bf2v r = __builtin_convertvector(v, bf2v); return __builtin_bit_cast(unsigned, r); }
; DI float bflo(unsigned w) { return __uint_as_float(w << 16); }
; DI float bfhi(unsigned w) { return __uint_as_float(w & 0xffff0000u); }
; #define LDS_WAIT() asm volatile("s_waitcnt lgkmcnt(0)" ::: "memory")
; DI void attn_item(const AttnItem& it, LAS unsigned char* wl, int lane) {
;     ...
;     lsum += __shfl_xor(lsum, 32);
;     const float inv = __fdividef(1.f, lsum);
;     if (qi < it.nq) {
;         bf16_t* zr = it.zo + (size_t)qi * it.zold + 4 * hh;
; #pragma unroll
;         for (int g = 0; g < 4; ++g) {
;             { const u32x2 z = *(const u32x2*)(zr + 8 * g); u32x2 w;
;               w.x = pk2(o0[4 * g] * inv * bflo(z.x), o0[4 * g + 1] * inv * bfhi(z.x)); w.y = pk2(o0[4 * g + 2] * inv * bflo(z.y), o0[4 * g + 3] * inv * bfhi(z.y));
;               *(u32x2*)(zr + 8 * g) = w; }
;             { const u32x2 z = *(const u32x2*)(zr + 32 + 8 * g); u32x2 w;
;               w.x = pk2(o1[4 * g] * inv * bflo(z.x), o1[4 * g + 1] * inv * bfhi(z.x)); w.y = pk2(o1[4 * g + 2] * inv * bflo(z.y), o1[4 * g + 3] * inv * bfhi(z.y));
;               *(u32x2*)(zr + 32 + 8 * g) = w; }
;         }
;     }
;     LDS_WAIT();
.Lat_novdma_22:
	v_mfma_f32_32x32x16_bf16 v[16:31], v[212:215], v[64:67], v[16:31]
	v_mfma_f32_32x32x16_bf16 v[32:47], v[216:219], v[64:67], v[32:47]
	v_mfma_f32_32x32x16_bf16 v[16:31], v[220:223], v[72:75], v[16:31]
	v_mfma_f32_32x32x16_bf16 v[32:47], v[224:227], v[72:75], v[32:47]
	s_add_i32 s71, s71, 1
	s_add_i32 s72, s72, 32
	s_sub_i32 s66, s66, 32
	s_cmp_lt_u32 s71, s65
	s_cbranch_scc1 .Lat_loop
.Lat_done:
	v_mov_b32_e32 v97, v99
	s_nop 1
	v_permlane32_swap_b32_e32 v99, v97
	v_add_f32_e32 v99, v99, v97
	v_rcp_f32_e32 v99, v99
	v_cmp_gt_u32_e32 vcc, s63, v108
	s_and_saveexec_b64 s[80:81], vcc
	s_cbranch_execz .Lat_skipst_24
	global_load_dwordx2 v[80:81], v245, s[56:57]
	global_load_dwordx2 v[82:83], v245, s[56:57] offset:16
	global_load_dwordx2 v[84:85], v245, s[56:57] offset:32
	global_load_dwordx2 v[86:87], v245, s[56:57] offset:48
	global_load_dwordx2 v[88:89], v245, s[56:57] offset:64
	global_load_dwordx2 v[90:91], v245, s[56:57] offset:80
	global_load_dwordx2 v[92:93], v245, s[56:57] offset:96
	global_load_dwordx2 v[94:95], v245, s[56:57] offset:112
	s_waitcnt vmcnt(7)
	v_mul_f32_e32 v16, v16, v99
	v_mul_f32_e32 v17, v17, v99
	v_mul_f32_e32 v18, v18, v99
	v_mul_f32_e32 v19, v19, v99
	v_lshlrev_b32_e32 v96, 16, v80
	v_and_b32_e32 v97, 0xffff0000, v80
	v_lshlrev_b32_e32 v100, 16, v81
	v_and_b32_e32 v101, 0xffff0000, v81
	v_mul_f32_e32 v16, v16, v96
	v_mul_f32_e32 v17, v17, v97
	v_mul_f32_e32 v18, v18, v100
	v_mul_f32_e32 v19, v19, v101
	v_cvt_pk_bf16_f32 v16, v16, v17
	v_cvt_pk_bf16_f32 v17, v18, v19
	global_store_dwordx2 v245, v[16:17], s[56:57]
	s_waitcnt vmcnt(7)
	v_mul_f32_e32 v20, v20, v99
	v_mul_f32_e32 v21, v21, v99
	v_mul_f32_e32 v22, v22, v99
	v_mul_f32_e32 v23, v23, v99
	v_lshlrev_b32_e32 v96, 16, v82
	v_and_b32_e32 v97, 0xffff0000, v82
	v_lshlrev_b32_e32 v100, 16, v83
	v_and_b32_e32 v101, 0xffff0000, v83
	v_mul_f32_e32 v20, v20, v96
	v_mul_f32_e32 v21, v21, v97
	v_mul_f32_e32 v22, v22, v100
	v_mul_f32_e32 v23, v23, v101
	v_cvt_pk_bf16_f32 v20, v20, v21
	v_cvt_pk_bf16_f32 v21, v22, v23
	global_store_dwordx2 v245, v[20:21], s[56:57] offset:16
	s_waitcnt vmcnt(7)
	v_mul_f32_e32 v24, v24, v99
	v_mul_f32_e32 v25, v25, v99
	v_mul_f32_e32 v26, v26, v99
	v_mul_f32_e32 v27, v27, v99
	v_lshlrev_b32_e32 v96, 16, v84
	v_and_b32_e32 v97, 0xffff0000, v84
	v_lshlrev_b32_e32 v100, 16, v85
	v_and_b32_e32 v101, 0xffff0000, v85
	v_mul_f32_e32 v24, v24, v96
	v_mul_f32_e32 v25, v25, v97
	v_mul_f32_e32 v26, v26, v100
	v_mul_f32_e32 v27, v27, v101
	v_cvt_pk_bf16_f32 v24, v24, v25
	v_cvt_pk_bf16_f32 v25, v26, v27
	global_store_dwordx2 v245, v[24:25], s[56:57] offset:32
	s_waitcnt vmcnt(7)
	v_mul_f32_e32 v28, v28, v99
	v_mul_f32_e32 v29, v29, v99
	v_mul_f32_e32 v30, v30, v99
	v_mul_f32_e32 v31, v31, v99
	v_lshlrev_b32_e32 v96, 16, v86
	v_and_b32_e32 v97, 0xffff0000, v86
	v_lshlrev_b32_e32 v100, 16, v87
	v_and_b32_e32 v101, 0xffff0000, v87
	v_mul_f32_e32 v28, v28, v96
	v_mul_f32_e32 v29, v29, v97
	v_mul_f32_e32 v30, v30, v100
	v_mul_f32_e32 v31, v31, v101
	v_cvt_pk_bf16_f32 v28, v28, v29
	v_cvt_pk_bf16_f32 v29, v30, v31
	global_store_dwordx2 v245, v[28:29], s[56:57] offset:48
	s_waitcnt vmcnt(7)
	v_mul_f32_e32 v32, v32, v99
	v_mul_f32_e32 v33, v33, v99
	v_mul_f32_e32 v34, v34, v99
	v_mul_f32_e32 v35, v35, v99
	v_lshlrev_b32_e32 v96, 16, v88
	v_and_b32_e32 v97, 0xffff0000, v88
	v_lshlrev_b32_e32 v100, 16, v89
	v_and_b32_e32 v101, 0xffff0000, v89
	v_mul_f32_e32 v32, v32, v96
	v_mul_f32_e32 v33, v33, v97
	v_mul_f32_e32 v34, v34, v100
	v_mul_f32_e32 v35, v35, v101
	v_cvt_pk_bf16_f32 v32, v32, v33
	v_cvt_pk_bf16_f32 v33, v34, v35
	global_store_dwordx2 v245, v[32:33], s[56:57] offset:64
	s_waitcnt vmcnt(7)
	v_mul_f32_e32 v36, v36, v99
	v_mul_f32_e32 v37, v37, v99
	v_mul_f32_e32 v38, v38, v99
	v_mul_f32_e32 v39, v39, v99
	v_lshlrev_b32_e32 v96, 16, v90
	v_and_b32_e32 v97, 0xffff0000, v90
	v_lshlrev_b32_e32 v100, 16, v91
	v_and_b32_e32 v101, 0xffff0000, v91
	v_mul_f32_e32 v36, v36, v96
	v_mul_f32_e32 v37, v37, v97
	v_mul_f32_e32 v38, v38, v100
	v_mul_f32_e32 v39, v39, v101
	v_cvt_pk_bf16_f32 v36, v36, v37
	v_cvt_pk_bf16_f32 v37, v38, v39
	global_store_dwordx2 v245, v[36:37], s[56:57] offset:80
	s_waitcnt vmcnt(7)
	v_mul_f32_e32 v40, v40, v99
	v_mul_f32_e32 v41, v41, v99
	v_mul_f32_e32 v42, v42, v99
	v_mul_f32_e32 v43, v43, v99
	v_lshlrev_b32_e32 v96, 16, v92
	v_and_b32_e32 v97, 0xffff0000, v92
	v_lshlrev_b32_e32 v100, 16, v93
	v_and_b32_e32 v101, 0xffff0000, v93
	v_mul_f32_e32 v40, v40, v96
	v_mul_f32_e32 v41, v41, v97
	v_mul_f32_e32 v42, v42, v100
	v_mul_f32_e32 v43, v43, v101
	v_cvt_pk_bf16_f32 v40, v40, v41
	v_cvt_pk_bf16_f32 v41, v42, v43
	global_store_dwordx2 v245, v[40:41], s[56:57] offset:96
	s_waitcnt vmcnt(7)
	v_mul_f32_e32 v44, v44, v99
	v_mul_f32_e32 v45, v45, v99
	v_mul_f32_e32 v46, v46, v99
	v_mul_f32_e32 v47, v47, v99
	v_lshlrev_b32_e32 v96, 16, v94
	v_and_b32_e32 v97, 0xffff0000, v94
	v_lshlrev_b32_e32 v100, 16, v95
	v_and_b32_e32 v101, 0xffff0000, v95
	v_mul_f32_e32 v44, v44, v96
	v_mul_f32_e32 v45, v45, v97
	v_mul_f32_e32 v46, v46, v100
	v_mul_f32_e32 v47, v47, v101
	v_cvt_pk_bf16_f32 v44, v44, v45
	v_cvt_pk_bf16_f32 v45, v46, v47
	global_store_dwordx2 v245, v[44:45], s[56:57] offset:112
.Lat_skipst_24:
	s_or_b64 exec, exec, s[80:81]
	s_cmp_eq_u32 s69, 0
	s_cbranch_scc1 .Lat_ret_band
	s_branch .Lat_ret_mem
.Lat_ret_band:
	s_mov_b64 s[4:5], exec
	s_branch .LBB0_936

; DI void p2_mixers(const Params& p, LAS unsigned char* lds) {
;     ...
;             AttnItem a;
;             a.qld = 256; a.kld = 256; a.zold = 256; a.vtld = 256; a.nkeys = 256; a.nkb = 8; a.bias = nullptr; a.qpos0 = 0;
;             if (it < 2048) {
;                 const int head = it & 3, tg = it >> 2, tq = 32 * tg, b = tq >> 13;
;                 a.q = (const bf16_t*)(ws + OFF_QM) + (size_t)tq * 256 + head * 64; a.nq = 32;
;                 a.k = (const bf16_t*)(ws + OFF_MK) + (size_t)b * 65536 + head * 64;
;                 a.vt = (const bf16_t*)(ws + OFF_MVT) + (size_t)(b * 256 + head * 64) * 256;
;                 a.zo = (bf16_t*)(ws + OFF_ZM) + (size_t)tq * 256 + head * 64;
;             } else {
;                 const int j = it - 2048, head = j & 3, sb = j >> 2, tq = T_P + 16 * sb;
;                 a.q = (const bf16_t*)(ws + OFF_QM) + (size_t)tq * 256 + head * 64; a.nq = 16;
;                 a.k = (const bf16_t*)(ws + OFF_MKS) + (size_t)sb * 65536 + head * 64;
;                 a.vt = (const bf16_t*)(ws + OFF_MVST) + (size_t)(sb * 256 + head * 64) * 256;
;                 a.zo = (bf16_t*)(ws + OFF_ZM) + (size_t)tq * 256 + head * 64;
;             }
;             attn_item(a, wl, lane);
.LBB0_982:
	s_and_b64 vcc, exec, s[12:13]
	s_cbranch_vccz .LBB0_987
	s_cmpk_gt_i32 s39, 0x7ff
	s_cbranch_scc1 .Lat_mem_s2_1001
	s_and_b32 s12, s39, 3
	s_lshr_b32 s13, s39, 2
	s_lshl_b32 s19, s13, 5
	s_lshr_b32 s15, s19, 13
	s_lshl_b32 s21, s12, 7
	s_lshl_b32 s32, s15, 17
	s_add_i32 s32, s32, s21
	s_add_u32 s52, s44, 0xead0000
	s_addc_u32 s53, s45, 0
	s_add_u32 s52, s52, s32
	s_addc_u32 s53, s53, 0
	s_lshl_b32 s32, s15, 8
	s_lshl_b32 s14, s12, 6
	s_add_i32 s32, s32, s14
	s_lshl_b32 s32, s32, 9
	s_add_u32 s54, s44, 0xeb10000
	s_addc_u32 s55, s45, 0
	s_add_u32 s54, s54, s32
	s_addc_u32 s55, s55, 0
	s_mov_b32 s63, 32
	s_branch .Lat_mem_done_1002
.Lat_mem_s2_1001:
	s_add_i32 s13, s39, 0xfffff800
	s_and_b32 s12, s13, 3
	s_lshr_b32 s14, s13, 2
	s_lshl_b32 s19, s14, 4
	s_add_i32 s19, s19, 0x4000
	s_lshl_b32 s21, s12, 7
	s_lshl_b32 s32, s14, 17
	s_add_i32 s32, s32, s21
	s_add_u32 s52, s44, 0xeb50000
	s_addc_u32 s53, s45, 0
	s_add_u32 s52, s52, s32
	s_addc_u32 s53, s53, 0
	s_lshl_b32 s32, s14, 8
	s_lshl_b32 s15, s12, 6
	s_add_i32 s32, s32, s15
	s_lshl_b32 s32, s32, 9
	s_add_u32 s54, s44, 0xef50000
	s_addc_u32 s55, s45, 0
	s_add_u32 s54, s54, s32
	s_addc_u32 s55, s55, 0
	s_mov_b32 s63, 16
.Lat_mem_done_1002:
	s_lshl_b32 s32, s19, 9
	s_add_i32 s32, s32, s21
	s_add_u32 s50, s44, 0xda50000
	s_addc_u32 s51, s45, 0
	s_add_u32 s50, s50, s32
	s_addc_u32 s51, s51, 0
	s_add_u32 s56, s44, 0xe290000
	s_addc_u32 s57, s45, 0
	s_add_u32 s56, s56, s32
	s_addc_u32 s57, s57, 0
	s_movk_i32 s64, 0x100
	s_mov_b32 s65, 8
	s_mov_b32 s66, 0x7fff0000
	s_movk_i32 s58, 0x200
	s_movk_i32 s59, 0x200
	s_movk_i32 s84, 0x40
	s_mov_b32 s67, 0
	s_mov_b32 s68, 0
	s_mov_b32 s69, 1
	s_branch .Lat_entry

; DI void p2_mixers(const Params& p, LAS unsigned char* lds) {
;     ...
;         for (int k = 0;; ++k) {
;             int it;
;             if (NGW == 2048) { if (k >= 2) break; it = k ? m1 : m0; if (it < 0) continue; }
;             else { it = gw + k * NGW; if (it >= 2176) break; }
;             AttnItem a;
;             a.qld = 256; a.kld = 256; a.zold = 256; a.vtld = 256; a.nkeys = 256; a.nkb = 8; a.bias = nullptr; a.qpos0 = 0;
;             if (it < 2048) {
;                 const int head = it & 3, tg = it >> 2, tq = 32 * tg, b = tq >> 13;
;                 a.q = (const bf16_t*)(ws + OFF_QM) + (size_t)tq * 256 + head * 64; a.nq = 32;
;                 a.k = (const bf16_t*)(ws + OFF_MK) + (size_t)b * 65536 + head * 64;
;                 a.vt = (const bf16_t*)(ws + OFF_MVT) + (size_t)(b * 256 + head * 64) * 256;
;                 a.zo = (bf16_t*)(ws + OFF_ZM) + (size_t)tq * 256 + head * 64;
;             } else {
;                 const int j = it - 2048, head = j & 3, sb = j >> 2, tq = T_P + 16 * sb;
;                 a.q = (const bf16_t*)(ws + OFF_QM) + (size_t)tq * 256 + head * 64; a.nq = 16;
;                 a.k = (const bf16_t*)(ws + OFF_MKS) + (size_t)sb * 65536 + head * 64;
;                 a.vt = (const bf16_t*)(ws + OFF_MVST) + (size_t)(sb * 256 + head * 64) * 256;
;                 a.zo = (bf16_t*)(ws + OFF_ZM) + (size_t)tq * 256 + head * 64;
;             }
;             attn_item(a, wl, lane);
;         }
.Lat_ret_mem:
	s_mov_b64 s[14:15], exec
